# attention main loop: first PV group's transposed V reads hoisted above the softmax packing (first half only)
# speedup vs baseline: 1.0014x; 1.0014x over previous
.LBB0_453:
	ds_read_b128 v[66:69], v209 offset:49152
	ds_read_b128 v[70:73], v209 offset:57344
	ds_read_b128 v[232:235], v214 offset:49152
	ds_read_b128 v[236:239], v214 offset:57344
	ds_read_b128 v[200:203], v213 offset:49152
	ds_read_b128 v[204:207], v213 offset:57344
	v_add_f32_e32 v164, 0, v165
	v_add_f32_e32 v164, v179, v164
	s_waitcnt lgkmcnt(5)
	v_mfma_f32_32x32x16_bf16 v[82:97], v[66:69], v[120:123], 0
	v_add_f32_e32 v164, v166, v164
	v_add_f32_e32 v164, v221, v164
	v_add_f32_e32 v164, v178, v164
	v_add_f32_e32 v164, v231, v164
	v_add_f32_e32 v164, v167, v164
	v_add_f32_e32 v164, v177, v164
	v_add_f32_e32 v164, v173, v164
	s_waitcnt lgkmcnt(4)
	v_mfma_f32_32x32x16_bf16 v[66:81], v[70:73], v[120:123], 0
	v_add_f32_e32 v164, v175, v164
	v_add_f32_e32 v164, v174, v164
	v_add_f32_e32 v164, v176, v164
	v_exp_f32_e32 v162, v162
	v_add_f32_e32 v164, v169, v164
	v_exp_f32_e32 v163, v163
	v_add_f32_e32 v164, v171, v164
	s_waitcnt lgkmcnt(3)
	v_mfma_f32_32x32x16_bf16 v[82:97], v[232:235], v[112:115], v[82:97]
	v_exp_f32_e32 v160, v160
	v_add_f32_e32 v164, v170, v164
	v_exp_f32_e32 v161, v161
	v_add_f32_e32 v164, v172, v164
	v_exp_f32_e32 v156, v156
	v_add_f32_e32 v164, v162, v164
	v_exp_f32_e32 v157, v157
	s_waitcnt lgkmcnt(2)
	v_mfma_f32_32x32x16_bf16 v[66:81], v[236:239], v[112:115], v[66:81]
	ds_read_b128 v[232:235], v212 offset:49152
	ds_read_b128 v[236:239], v212 offset:57344
	v_add_f32_e32 v164, v163, v164
	v_exp_f32_e32 v152, v152
	v_add_f32_e32 v164, v160, v164
	v_exp_f32_e32 v153, v153
	v_add_f32_e32 v164, v161, v164
	v_exp_f32_e32 v150, v150
	s_waitcnt lgkmcnt(3)
	v_mfma_f32_32x32x16_bf16 v[82:97], v[200:203], v[128:131], v[82:97]
	v_add_f32_e32 v164, v156, v164
	v_exp_f32_e32 v151, v151
	v_add_f32_e32 v164, v157, v164
	v_exp_f32_e32 v158, v158
	v_add_f32_e32 v164, v152, v164
	v_exp_f32_e32 v159, v159
	v_add_f32_e32 v164, v153, v164
	s_waitcnt lgkmcnt(2)
	v_mfma_f32_32x32x16_bf16 v[66:81], v[204:207], v[128:131], v[66:81]
	ds_read_b128 v[200:203], v211 offset:49152
	ds_read_b128 v[204:207], v211 offset:57344
	v_exp_f32_e32 v154, v154
	v_add_f32_e32 v164, v150, v164
	v_exp_f32_e32 v155, v155
	v_add_f32_e32 v164, v151, v164
	v_exp_f32_e32 v148, v148
	v_add_f32_e32 v164, v158, v164
	s_waitcnt lgkmcnt(3)
	v_mfma_f32_32x32x16_bf16 v[82:97], v[232:235], v[124:127], v[82:97]
	v_exp_f32_e32 v149, v149
	v_add_f32_e32 v164, v159, v164
	v_add_f32_e32 v164, v154, v164
	v_add_f32_e32 v164, v155, v164
	v_add_f32_e32 v164, v148, v164
	v_add_f32_e32 v218, v149, v164
	v_mov_b32_e32 v219, v218
	s_waitcnt lgkmcnt(2)
	v_mfma_f32_32x32x16_bf16 v[66:81], v[236:239], v[124:127], v[66:81]
	ds_read_b128 v[232:235], v210 offset:49152
	ds_read_b128 v[236:239], v210 offset:57344
	v_permlane32_swap_b32_e32 v218, v219
	s_waitcnt lgkmcnt(3)
	v_mfma_f32_32x32x16_bf16 v[82:97], v[200:203], v[116:119], v[82:97]
	s_waitcnt lgkmcnt(2)
	v_mfma_f32_32x32x16_bf16 v[66:81], v[204:207], v[116:119], v[66:81]
	ds_read_b128 v[200:203], v216 offset:49152
	ds_read_b128 v[204:207], v216 offset:57344
	s_waitcnt lgkmcnt(3)
	v_mfma_f32_32x32x16_bf16 v[82:97], v[232:235], v[108:111], v[82:97]
	s_waitcnt lgkmcnt(2)
	v_mfma_f32_32x32x16_bf16 v[66:81], v[236:239], v[108:111], v[66:81]
	ds_read_b128 v[232:235], v215 offset:49152
	ds_read_b128 v[236:239], v215 offset:57344
	s_waitcnt lgkmcnt(3)
	v_mfma_f32_32x32x16_bf16 v[82:97], v[200:203], v[104:107], v[82:97]
	s_waitcnt lgkmcnt(2)
	v_mfma_f32_32x32x16_bf16 v[66:81], v[204:207], v[104:107], v[66:81]
	v_cvt_pk_bf16_f32 v164, v165, v179
	v_cvt_pk_bf16_f32 v165, v166, v221
	v_cvt_pk_bf16_f32 v166, v178, v231
	v_cvt_pk_bf16_f32 v167, v167, v177
	v_cvt_pk_bf16_f32 v220, v173, v175
	v_cvt_pk_bf16_f32 v221, v174, v176
	s_waitcnt lgkmcnt(1)
	v_mfma_f32_32x32x16_bf16 v[82:97], v[232:235], v[100:103], v[82:97]
	v_cvt_pk_bf16_f32 v222, v169, v171
	v_permlane32_swap_b32_e32 v164, v166
	v_cvt_pk_bf16_f32 v223, v170, v172
	v_permlane32_swap_b32_e32 v220, v222
	v_cvt_pk_bf16_f32 v170, v162, v163
	s_waitcnt lgkmcnt(0)
	v_mfma_f32_32x32x16_bf16 v[66:81], v[236:239], v[100:103], v[66:81]
	ds_read_b64_tr_b16 v[232:233], v192 offset:0
	ds_read_b64_tr_b16 v[234:235], v192 offset:0x800
	ds_read_b64_tr_b16 v[236:237], v192 offset:0x1000
	ds_read_b64_tr_b16 v[238:239], v192 offset:0x1800
	ds_read_b64_tr_b16 v[240:241], v192 offset:0x2000
	ds_read_b64_tr_b16 v[242:243], v192 offset:0x2800
	ds_read_b64_tr_b16 v[244:245], v192 offset:0x3000
	ds_read_b64_tr_b16 v[246:247], v192 offset:0x3800
	v_cvt_pk_bf16_f32 v171, v160, v161
	v_cvt_pk_bf16_f32 v172, v156, v157
	v_cvt_pk_bf16_f32 v173, v152, v153
	v_cvt_pk_bf16_f32 v174, v150, v151
	v_cvt_pk_bf16_f32 v175, v158, v159
	v_cvt_pk_bf16_f32 v176, v154, v155
	v_cvt_pk_bf16_f32 v177, v148, v149
	v_permlane32_swap_b32_e32 v165, v167
	v_permlane32_swap_b32_e32 v221, v223
	v_permlane32_swap_b32_e32 v170, v172
	v_permlane32_swap_b32_e32 v171, v173
	v_permlane32_swap_b32_e32 v174, v176
	v_permlane32_swap_b32_e32 v175, v177
	v_add_co_u32_e32 v148, vcc, s1, v180
	s_nop 1
	v_addc_co_u32_e32 v149, vcc, -1, v181, vcc
	v_add_co_u32_e32 v152, vcc, s28, v180
	s_nop 1
	v_addc_co_u32_e32 v153, vcc, -1, v181, vcc
	v_add_co_u32_e32 v156, vcc, s19, v180
	global_load_dwordx4 v[148:151], v[148:149], off
	s_nop 0
	global_load_dwordx4 v[152:155], v[152:153], off
	v_addc_co_u32_e32 v157, vcc, -1, v181, vcc
	v_add_co_u32_e32 v160, vcc, s27, v180
	s_nop 1
	v_addc_co_u32_e32 v161, vcc, -1, v181, vcc
	global_load_dwordx4 v[156:159], v[156:157], off
	s_nop 0
	global_load_dwordx4 v[160:163], v[160:161], off
	s_waitcnt lgkmcnt(0)
	s_nop 0
	v_mfma_f32_32x32x16_bf16 v[2:17], v[164:167], v[232:235], v[2:17]
	ds_read_b64_tr_b16 v[232:233], v192 offset:0x200
	ds_read_b64_tr_b16 v[234:235], v192 offset:0xa00
	v_mfma_f32_32x32x16_bf16 v[2:17], v[220:223], v[236:239], v[2:17]
	ds_read_b64_tr_b16 v[236:237], v192 offset:0x1200
	ds_read_b64_tr_b16 v[238:239], v192 offset:0x1a00
	v_mfma_f32_32x32x16_bf16 v[2:17], v[170:173], v[240:243], v[2:17]
	ds_read_b64_tr_b16 v[240:241], v192 offset:0x2200
	ds_read_b64_tr_b16 v[242:243], v192 offset:0x2a00
	v_mfma_f32_32x32x16_bf16 v[2:17], v[174:177], v[244:247], v[2:17]
	ds_read_b64_tr_b16 v[244:245], v192 offset:0x3200
	ds_read_b64_tr_b16 v[246:247], v192 offset:0x3a00
	s_waitcnt lgkmcnt(0)
	v_mfma_f32_32x32x16_bf16 v[50:65], v[164:167], v[232:235], v[50:65]
	ds_read_b64_tr_b16 v[232:233], v192 offset:0x400
	ds_read_b64_tr_b16 v[234:235], v192 offset:0xc00
	v_mfma_f32_32x32x16_bf16 v[50:65], v[220:223], v[236:239], v[50:65]
	ds_read_b64_tr_b16 v[236:237], v192 offset:0x1400
	ds_read_b64_tr_b16 v[238:239], v192 offset:0x1c00
	v_mfma_f32_32x32x16_bf16 v[50:65], v[170:173], v[240:243], v[50:65]
	ds_read_b64_tr_b16 v[240:241], v192 offset:0x2400
	ds_read_b64_tr_b16 v[242:243], v192 offset:0x2c00
	v_mfma_f32_32x32x16_bf16 v[50:65], v[174:177], v[244:247], v[50:65]
	ds_read_b64_tr_b16 v[244:245], v192 offset:0x3400
	ds_read_b64_tr_b16 v[246:247], v192 offset:0x3c00
	s_waitcnt lgkmcnt(0)
	v_mfma_f32_32x32x16_bf16 v[34:49], v[164:167], v[232:235], v[34:49]
	ds_read_b64_tr_b16 v[232:233], v192 offset:0x600
	ds_read_b64_tr_b16 v[234:235], v192 offset:0xe00
	v_mfma_f32_32x32x16_bf16 v[34:49], v[220:223], v[236:239], v[34:49]
	ds_read_b64_tr_b16 v[236:237], v192 offset:0x1600
	ds_read_b64_tr_b16 v[238:239], v192 offset:0x1e00
	v_mfma_f32_32x32x16_bf16 v[34:49], v[170:173], v[240:243], v[34:49]
	ds_read_b64_tr_b16 v[240:241], v192 offset:0x2600
	ds_read_b64_tr_b16 v[242:243], v192 offset:0x2e00
	v_mfma_f32_32x32x16_bf16 v[34:49], v[174:177], v[244:247], v[34:49]
	ds_read_b64_tr_b16 v[244:245], v192 offset:0x3600
	ds_read_b64_tr_b16 v[246:247], v192 offset:0x3e00
	s_waitcnt lgkmcnt(0)
	v_mfma_f32_32x32x16_bf16 v[18:33], v[164:167], v[232:235], v[18:33]
	v_max_f32_e32 v164, v83, v83
	v_max_f32_e32 v165, v82, v82
	v_max_f32_e32 v164, v165, v164
	v_max3_f32 v164, v164, v84, v85
	v_max3_f32 v164, v164, v86, v87
	v_max3_f32 v164, v164, v88, v89
	v_max3_f32 v164, v164, v90, v91
	v_max3_f32 v164, v164, v92, v93
	v_max3_f32 v164, v164, v94, v95
	v_mfma_f32_32x32x16_bf16 v[18:33], v[220:223], v[236:239], v[18:33]
	v_max3_f32 v164, v164, v96, v97
	v_max3_f32 v164, v164, v66, v67
	v_max3_f32 v164, v164, v68, v69
	v_max3_f32 v164, v164, v70, v71
	v_max3_f32 v164, v164, v72, v73
	v_max3_f32 v164, v164, v74, v75
	v_max3_f32 v164, v164, v76, v77
	v_max3_f32 v164, v164, v78, v79
	v_mfma_f32_32x32x16_bf16 v[18:33], v[170:173], v[240:243], v[18:33]
	v_max3_f32 v164, v164, v80, v81
	v_mov_b32_e32 v165, v164
	s_nop 1
	v_permlane32_swap_b32_e32 v164, v165
	v_max_f32_e32 v165, v165, v165
	v_max_f32_e32 v164, v164, v164
	v_max_f32_e32 v164, v164, v165
	v_sub_f32_e32 v165, v164, v168
	v_cmp_ge_f32_e32 vcc, s0, v165
	v_max_f32_e32 v165, v168, v168
	v_max_f32_e32 v164, v165, v164
	v_mfma_f32_32x32x16_bf16 v[18:33], v[174:177], v[244:247], v[18:33]
	v_sub_f32_e32 v165, v168, v164
	v_mul_f32_e32 v165, 0x3e0293ee, v165
	v_exp_f32_e32 v165, v165
	s_cmp_eq_u64 vcc, exec
	s_cselect_b64 s[42:43], -1, 0
	s_barrier
	s_waitcnt vmcnt(4)
	v_cndmask_b32_e64 v220, v165, 1.0, s[42:43]
	v_cmp_gt_f32_e32 vcc, 1.0, v220
	s_waitcnt vmcnt(7)
	ds_write_b128 v195, v[132:135]
	s_waitcnt vmcnt(6)
	ds_write_b128 v208, v[140:143]
	s_waitcnt vmcnt(5)
	ds_write_b128 v193, v[136:139] offset:32768
	s_waitcnt vmcnt(4)
	ds_write_b128 v194, v[144:147] offset:32768
	s_cbranch_vccz .LBB0_457
	s_and_saveexec_b64 s[4:5], s[40:41]
	ds_write_b32 v189, v220 offset:128
	s_or_b64 exec, exec, s[4:5]
	s_waitcnt lgkmcnt(0)
	v_add_u32_e32 v165, v188, v98
	ds_read_b128 v[170:173], v165 offset:224
	ds_read_b128 v[174:177], v165 offset:192
	ds_read_b128 v[232:235], v165 offset:160
	ds_read_b128 v[236:239], v165 offset:128
	s_waitcnt lgkmcnt(3)
	v_pk_mul_f32 v[14:15], v[14:15], v[170:171]
	s_waitcnt lgkmcnt(2)
	v_pk_mul_f32 v[10:11], v[10:11], v[174:175]
	s_waitcnt lgkmcnt(1)
	v_pk_mul_f32 v[6:7], v[6:7], v[232:233]
	v_pk_mul_f32 v[16:17], v[16:17], v[172:173]
	v_pk_mul_f32 v[12:13], v[12:13], v[176:177]
	v_pk_mul_f32 v[8:9], v[8:9], v[234:235]
	s_waitcnt lgkmcnt(0)
	v_pk_mul_f32 v[4:5], v[4:5], v[238:239]
	v_pk_mul_f32 v[2:3], v[2:3], v[236:237]
	v_pk_mul_f32 v[62:63], v[62:63], v[170:171]
	v_pk_mul_f32 v[58:59], v[58:59], v[174:175]
	v_pk_mul_f32 v[54:55], v[54:55], v[232:233]
	v_pk_mul_f32 v[64:65], v[64:65], v[172:173]
	v_pk_mul_f32 v[60:61], v[60:61], v[176:177]
	v_pk_mul_f32 v[56:57], v[56:57], v[234:235]
	v_pk_mul_f32 v[52:53], v[52:53], v[238:239]
	v_pk_mul_f32 v[50:51], v[50:51], v[236:237]
	v_pk_mul_f32 v[46:47], v[46:47], v[170:171]
	v_pk_mul_f32 v[42:43], v[42:43], v[174:175]
	v_pk_mul_f32 v[38:39], v[38:39], v[232:233]
	v_pk_mul_f32 v[48:49], v[48:49], v[172:173]
	v_pk_mul_f32 v[44:45], v[44:45], v[176:177]
	v_pk_mul_f32 v[40:41], v[40:41], v[234:235]
	v_pk_mul_f32 v[36:37], v[36:37], v[238:239]
	v_pk_mul_f32 v[34:35], v[34:35], v[236:237]
	v_pk_mul_f32 v[30:31], v[30:31], v[170:171]
	v_pk_mul_f32 v[26:27], v[26:27], v[174:175]
	v_pk_mul_f32 v[22:23], v[22:23], v[232:233]
	v_pk_mul_f32 v[32:33], v[32:33], v[172:173]
	v_pk_mul_f32 v[28:29], v[28:29], v[176:177]
	v_pk_mul_f32 v[24:25], v[24:25], v[234:235]
	v_pk_mul_f32 v[20:21], v[20:21], v[238:239]
	v_pk_mul_f32 v[18:19], v[18:19], v[236:237]
